# baseline (speedup 1.0000x reference)
; #define LAS __attribute__((address_space(3)))
; DI int otid() { int t = threadIdx.x; asm volatile("" : "+v"(t)); return t; }
; DI unsigned char* ows(const Params& P) { unsigned char* p = P.ws; asm volatile("" : "+s"(p)); return p; }
; #define ATT_LOAD(kr, vr, t) do { const bf16_t* kp_ = KVb + (size_t)(t) * 64 * 2048 + kn_off; \
;         kr[0] = *(const u32x4*)kp_; kr[1] = *(const u32x4*)(kp_ + 32 * 2048); kr[2] = *(const u32x4*)(KPEb + (t) * 64 * 64 + kp_off); \
;         const bf16_t* vp_ = VTb + (t) * 64 + v_off; vr[0] = *(const u32x4*)vp_; vr[1] = *(const u32x4*)(vp_ + 64 * SEQ); } while (0)
; DI void attn_unit(const Params& P, LAS unsigned char* lds, int b, int h, int qb, bool dry) {
;     const int tid = otid(), lane = tid & 63, w = __builtin_amdgcn_readfirstlane(tid >> 6), r = lane & 31, hh = lane >> 5;
;     bf16_t* Q = (bf16_t*)(ows(P) + OFF_Q);
;     const bf16_t* KV = (const bf16_t*)(ows(P) + OFF_KV); const bf16_t* KPE = (const bf16_t*)(ows(P) + OFF_KPE); const bf16_t* VT = (const bf16_t*)(ows(P) + OFF_U);
;     LAS unsigned char* Ks = lds; LAS unsigned char* Vs = lds + 2 * KS_BYTES;
;     const int q0 = qb * 256 + w * 32;
;     bf16_t* qrow = Q + ((size_t)b * SEQ + q0 + r) * 1536 + h * 192;
;     bf16x8 qf[12];
; #pragma unroll
;     for (int s = 0; s < 12; ++s) qf[s] = *(const bf16x8*)(qrow + 16 * s + 8 * hh);
;     f32x16 o[4];
; #pragma unroll
;     for (int d = 0; d < 4; ++d)
; #pragma unroll
;         for (int i = 0; i < 16; ++i) o[d][i] = 0.f;
;     float mrun = -INFINITY, lrun = 0.f;
;     const int nt = 4 * (qb + 1);
;     const bf16_t* KVb = KV + (size_t)b * SEQ * 2048 + h * 256; const bf16_t* KPEb = KPE + (size_t)b * SEQ * 64; const bf16_t* VTb = VT + (size_t)(b * 8 + h) * 128 * SEQ;
;     const int kn_off = (tid >> 4) * 2048 + (tid & 15) * 8, kn_dst = (tid >> 4) * KS_STRIDE + (tid & 15) * 16;
;     const int kp_off = (tid >> 3) * 64 + (tid & 7) * 8, kp_dst = (tid >> 3) * KS_STRIDE + 256 + (tid & 7) * 16;
;     const int v_off = (tid >> 3) * SEQ + (tid & 7) * 8, v_dst = (tid >> 3) * VS_STRIDE + (tid & 7) * 16;
;     ...
;     ATT_LOAD(kA, vA, 0);
;     __syncthreads();
;     ATT_STORE(kA, vA, 0);
;     ATT_LOAD(kA, vA, 1);
.LBB0_31:
	s_waitcnt vmcnt(0)
	v_mov_b32_e32 v2, v195
	s_load_dwordx8 s[64:71], s[84:85], 0xc8
	s_bfe_u32 s35, s55, 0x50003
	v_readfirstlane_b32 s49, v2
	s_xor_b32 s37, s35, 63
	s_ashr_i32 s3, s49, 1
	s_ashr_i32 s46, s55, 8
	s_lshl_b32 s2, s37, 8
	s_and_b32 s53, s3, 0xffffffe0
	s_and_b32 s48, s54, 7
	s_waitcnt lgkmcnt(0)
	s_mov_b64 s[60:61], s[64:65]
	s_add_i32 s53, s53, s2
	s_ashr_i32 s47, s46, 31
	s_lshl_b32 s52, s48, 9
	s_lshr_b32 s56, s55, 3
	s_and_b32 s42, s55, 7
	s_mov_b64 s[62:63], s[66:67]
	s_mov_b64 s[64:65], s[68:69]
	s_mov_b64 s[66:67], s[70:71]
	s_lshl_b64 s[2:3], s[46:47], 14
	s_ashr_i32 s20, s53, 31
	v_and_b32_e32 v23, 31, v2
	s_mov_b64 s[30:31], s[66:67]
	s_add_u32 s36, s2, s53
	v_or_b32_e32 v3, s36, v23
	v_mov_b64_e32 v[0:1], s[30:31]
	s_addc_u32 s20, s3, s20
	v_mad_u64_u32 v[0:1], s[30:31], v3, s39, v[0:1]
	s_mul_i32 s36, s42, 0xc0
	v_mad_i32_i24 v1, s20, v248, v1
	s_lshl_b32 s20, s36, 1
	s_lshl_b32 s62, s37, 2
	v_bfe_u32 v36, v2, 5, 1
	s_mov_b64 s[40:41], s[66:67]
	v_lshl_add_u64 v[0:1], v[0:1], 0, s[20:21]
	s_mov_b64 s[30:31], 0xd808000
	s_add_i32 s59, s62, 4
	s_lshl_b64 s[44:45], s[46:47], 26
	v_lshl_add_u64 v[186:187], v[0:1], 0, s[30:31]
	v_lshlrev_b32_e32 v184, 4, v36
	s_add_u32 s30, s40, s44
	s_mov_b64 s[26:27], s[66:67]
	s_mov_b64 s[50:51], s[66:67]
	v_lshl_add_u64 v[0:1], v[186:187], 0, v[184:185]
	s_addc_u32 s31, s41, s45
	s_lshl_b32 s37, s42, 8
	s_lshl_b32 s43, s42, 9
	v_and_b32_e32 v3, 15, v2
	global_load_dwordx4 v[96:99], v[0:1], off
	global_load_dwordx4 v[100:103], v[0:1], off offset:32
	global_load_dwordx4 v[104:107], v[0:1], off offset:64
	global_load_dwordx4 v[108:111], v[0:1], off offset:96
	global_load_dwordx4 v[112:115], v[0:1], off offset:128
	global_load_dwordx4 v[116:119], v[0:1], off offset:160
	global_load_dwordx4 v[120:123], v[0:1], off offset:192
	global_load_dwordx4 v[124:127], v[0:1], off offset:224
	global_load_dwordx4 v[128:131], v[0:1], off offset:256
	global_load_dwordx4 v[132:135], v[0:1], off offset:288
	global_load_dwordx4 v[136:139], v[0:1], off offset:320
	global_load_dwordx4 v[140:143], v[0:1], off offset:352
	s_add_u32 s80, s30, s43
	v_ashrrev_i32_e32 v1, 4, v2
	v_lshlrev_b32_e32 v0, 3, v3
	s_addc_u32 s81, s31, 0
	s_lshl_b32 s57, s46, 3
	v_lshl_or_b32 v0, v1, 11, v0
	v_mul_lo_u32 v1, v1, s29
	s_lshl_b64 s[30:31], s[46:47], 21
	s_or_b32 s46, s57, s42
	v_lshl_add_u32 v38, v3, 4, v1
	v_and_b32_e32 v1, 7, v2
	s_ashr_i32 s47, s46, 31
	v_ashrrev_i32_e32 v39, 3, v2
	v_lshlrev_b32_e32 v2, 3, v1
	v_lshlrev_b32_e32 v22, 4, v1
	v_ashrrev_i32_e32 v1, 31, v0
	s_lshl_b64 s[46:47], s[46:47], 22
	v_lshlrev_b64 v[0:1], 1, v[0:1]
	s_add_u32 s94, s50, s46
	v_lshl_add_u64 v[26:27], s[80:81], 0, v[0:1]
	s_mov_b32 s28, 0x13808000
	s_addc_u32 s95, s51, s47
	v_lshl_or_b32 v10, v39, 6, v2
	v_lshl_or_b32 v14, v39, 14, v2
	v_add_co_u32_e32 v2, vcc, s28, v26
	s_mov_b32 s28, 0x13828000
	s_nop 0
	v_addc_co_u32_e32 v3, vcc, 0, v27, vcc
	s_add_u32 s26, s26, s30
	v_add_co_u32_e32 v6, vcc, s28, v26
	v_ashrrev_i32_e32 v11, 31, v10
	s_addc_u32 s27, s27, s31
	v_ashrrev_i32_e32 v15, 31, v14
	v_addc_co_u32_e32 v7, vcc, 0, v27, vcc
	v_lshl_add_u64 v[28:29], v[10:11], 1, s[26:27]
	s_mov_b32 s26, 0xd408000
	v_lshlrev_b64 v[30:31], 1, v[14:15]
	v_add_co_u32_e32 v10, vcc, s26, v28
	v_lshl_add_u64 v[18:19], s[94:95], 0, v[30:31]
	s_mov_b64 s[26:27], 0x5808000
	v_addc_co_u32_e32 v11, vcc, 0, v29, vcc
	v_lshl_add_u64 v[32:33], v[18:19], 0, s[26:27]
	s_mov_b32 s26, 0x5808000
	v_add_co_u32_e32 v14, vcc, s26, v18
	global_load_dwordx4 v[2:5], v[2:3], off
	s_nop 0
	v_addc_co_u32_e32 v15, vcc, 0, v19, vcc
	s_mov_b32 s26, 0x5a08000
	global_load_dwordx4 v[6:9], v[6:7], off
	v_add_co_u32_e32 v34, vcc, s26, v18
	global_load_dwordx4 v[10:13], v[10:11], off
	s_nop 0
	v_addc_co_u32_e32 v35, vcc, 0, v19, vcc
	global_load_dwordx4 v[14:17], v[14:15], off
	s_movk_i32 s68, 0x88
	global_load_dwordx4 v[18:21], v[34:35], off
	v_mad_u64_u32 v[24:25], s[96:97], v39, s68, v[22:23]
	v_add_u32_e32 v250, 0, v38
	s_movk_i32 s26, 0x108
	s_waitcnt lgkmcnt(0)
	s_barrier
; #define ATT_LOAD(kr, vr, t) do { const bf16_t* kp_ = KVb + (size_t)(t) * 64 * 2048 + kn_off; \
;         kr[0] = *(const u32x4*)kp_; kr[1] = *(const u32x4*)(kp_ + 32 * 2048); kr[2] = *(const u32x4*)(KPEb + (t) * 64 * 64 + kp_off); \
;         const bf16_t* vp_ = VTb + (t) * 64 + v_off; vr[0] = *(const u32x4*)vp_; vr[1] = *(const u32x4*)(vp_ + 64 * SEQ); } while (0)
; DI void attn_unit(const Params& P, LAS unsigned char* lds, int b, int h, int qb, bool dry) {
;     ...
;     f32x16 o[4];
; #pragma unroll
;     for (int d = 0; d < 4; ++d)
; #pragma unroll
;         for (int i = 0; i < 16; ++i) o[d][i] = 0.f;
;     float mrun = -INFINITY, lrun = 0.f;
;     const int nt = 4 * (qb + 1);
;     const bf16_t* KVb = KV + (size_t)b * SEQ * 2048 + h * 256; const bf16_t* KPEb = KPE + (size_t)b * SEQ * 64; const bf16_t* VTb = VT + (size_t)(b * 8 + h) * 128 * SEQ;
;     const int kn_off = (tid >> 4) * 2048 + (tid & 15) * 8, kn_dst = (tid >> 4) * KS_STRIDE + (tid & 15) * 16;
;     const int kp_off = (tid >> 3) * 64 + (tid & 7) * 8, kp_dst = (tid >> 3) * KS_STRIDE + 256 + (tid & 7) * 16;
;     const int v_off = (tid >> 3) * SEQ + (tid & 7) * 8, v_dst = (tid >> 3) * VS_STRIDE + (tid & 7) * 16;
;     ...
;     ATT_LOAD(kA, vA, 0);
;     __syncthreads();
;     ATT_STORE(kA, vA, 0);
;     ATT_LOAD(kA, vA, 1);
;     __syncthreads();
;     for (int kt = 0; kt < nt; kt += 2) {
;         const bool more2 = kt + 2 < nt;
;         if (more2) ATT_LOAD(kB, vB, kt + 2);
	s_waitcnt vmcnt(0)
	ds_write_b128 v250, v[2:5]
	ds_write_b128 v250, v[6:9] offset:12800
	v_mad_u64_u32 v[2:3], s[26:27], v39, s26, v[24:25]
	v_add_u32_e32 v252, 0, v24
	s_mov_b32 s26, 0x13848000
	v_add_u32_e32 v251, 0, v2
	v_add_u32_e32 v253, 0xc800, v252
	v_add_u32_e32 v254, 0xea00, v252
	v_add_co_u32_e32 v2, vcc, s26, v26
	ds_write_b128 v251, v[10:13] offset:256
	ds_write2_b64 v253, v[14:15], v[16:17] offset1:1
	ds_write2_b64 v254, v[18:19], v[20:21] offset1:1
	v_addc_co_u32_e32 v3, vcc, 0, v27, vcc
	s_mov_b32 s26, 0x13868000
	global_load_dwordx4 v[144:147], v[2:3], off
	v_add_co_u32_e32 v2, vcc, s26, v26
	s_mov_b32 s26, 0xd40a000
	s_nop 0
	v_addc_co_u32_e32 v3, vcc, 0, v27, vcc
	global_load_dwordx4 v[148:151], v[2:3], off
	v_add_co_u32_e32 v2, vcc, s26, v28
	s_or_b32 s48, s57, s48
	s_nop 0
	v_addc_co_u32_e32 v3, vcc, 0, v29, vcc
	global_load_dwordx4 v[152:155], v[2:3], off
	global_load_dwordx4 v[156:159], v[32:33], off offset:128
	global_load_dwordx4 v[160:163], v[34:35], off offset:128
	s_ashr_i32 s26, s49, 7
	s_ashr_i32 s49, s48, 31
	s_lshl_b64 s[48:49], s[48:49], 22
	s_add_u32 s50, s50, s48
	v_mad_u32_u24 v213, v23, s29, 0
	s_movk_i32 s27, 0xfef8
	s_addc_u32 s51, s51, s49
	s_or_b32 s57, s44, s52
	v_mad_i32_i24 v18, v23, s27, v213
	v_readlane_b32 s27, v246, 47
	s_add_u32 s40, s40, s57
	v_mad_u64_u32 v[16:17], s[80:81], v39, s29, v[22:23]
	v_mov_b32_e32 v2, s27
	s_mov_b64 s[42:43], 0xd40e000
	s_addc_u32 s41, s41, s45
	v_lshlrev_b32_e32 v37, 3, v36
	v_readlane_b32 s96, v246, 55
	v_mad_u32_u24 v17, v23, s68, v2
	v_lshl_add_u64 v[188:189], v[28:29], 0, s[42:43]
	v_lshl_add_u64 v[2:3], s[50:51], 0, v[30:31]
	s_mov_b64 s[42:43], 0x5a08180
	v_lshl_add_u64 v[0:1], s[40:41], 0, v[0:1]
	s_mov_b64 s[40:41], 0x138e8000
	v_mov_b32_e32 v14, v185
	v_mov_b32_e32 v15, v185
	v_readlane_b32 s97, v246, 56
	v_readlane_b32 s94, v246, 63
	v_or_b32_e32 v214, s53, v23
	v_lshlrev_b32_e32 v212, 2, v36
	v_lshl_add_u64 v[190:191], v[2:3], 0, s[42:43]
	v_lshl_add_u64 v[192:193], v[0:1], 0, s[40:41]
	s_add_i32 s40, s26, s62
	v_mov_b32_e32 v0, v185
	v_mov_b32_e32 v1, v185
	v_mov_b32_e32 v2, v185
	v_mov_b32_e32 v3, v185
	v_mov_b32_e32 v4, v185
	v_mov_b32_e32 v5, v185
	v_mov_b32_e32 v6, v185
	v_mov_b32_e32 v7, v185
	v_mov_b32_e32 v8, v185
	v_mov_b32_e32 v9, v185
	v_mov_b32_e32 v10, v185
	v_mov_b32_e32 v11, v185
	v_mov_b32_e32 v12, v185
	v_mov_b32_e32 v13, v185
	v_add_u32_e32 v216, v18, v37
	v_add_u32_e32 v217, 0, v16
	v_add_u32_e32 v218, v17, v37
	v_mov_b64_e32 v[30:31], v[14:15]
	v_mov_b64_e32 v[46:47], v[14:15]
	v_mov_b64_e32 v[62:63], v[14:15]
	s_mov_b32 s20, 2
	v_readlane_b32 s98, v246, 57
	v_readlane_b32 s95, v245, 0
	v_readlane_b32 s71, v246, 62
	v_readlane_b32 s69, v246, 61
	s_mov_b32 s81, 0x14000
	v_readlane_b32 s28, v246, 54
	s_mov_b32 s58, s45
	s_sub_i32 s27, 1, s40
	s_sub_i32 s62, 0, s62
	s_sub_i32 s63, 0, s40
	v_mov_b32_e32 v194, 0xff800000
	v_mov_b32_e32 v196, 0
	v_mov_b32_e32 v197, 0
	v_mov_b32_e32 v198, 0
	v_mov_b32_e32 v199, 0
	v_mov_b32_e32 v200, 0
	v_mov_b32_e32 v201, 0
	v_mov_b32_e32 v202, 0
	v_mov_b32_e32 v203, 0
	v_mov_b32_e32 v204, 0
	v_mov_b32_e32 v205, 0
	v_mov_b32_e32 v206, 0
	v_mov_b32_e32 v207, 0
	v_mov_b32_e32 v208, 0
	v_mov_b32_e32 v209, 0
	v_mov_b32_e32 v210, 0
	v_mov_b32_e32 v211, 0
	v_mov_b32_e32 v215, 0
	v_mov_b32_e32 v219, v212
	v_mov_b64_e32 v[28:29], v[12:13]
	v_mov_b64_e32 v[26:27], v[10:11]
	v_mov_b64_e32 v[24:25], v[8:9]
	v_mov_b64_e32 v[22:23], v[6:7]
	v_mov_b64_e32 v[20:21], v[4:5]
	v_mov_b64_e32 v[18:19], v[2:3]
	v_mov_b64_e32 v[16:17], v[0:1]
	v_mov_b64_e32 v[44:45], v[12:13]
	v_mov_b64_e32 v[42:43], v[10:11]
	v_mov_b64_e32 v[40:41], v[8:9]
	v_mov_b64_e32 v[38:39], v[6:7]
	v_mov_b64_e32 v[36:37], v[4:5]
	v_mov_b64_e32 v[34:35], v[2:3]
	v_mov_b64_e32 v[32:33], v[0:1]
	v_mov_b64_e32 v[60:61], v[12:13]
	v_mov_b64_e32 v[58:59], v[10:11]
	v_mov_b64_e32 v[56:57], v[8:9]
	v_mov_b64_e32 v[54:55], v[6:7]
	v_mov_b64_e32 v[52:53], v[4:5]
	v_mov_b64_e32 v[50:51], v[2:3]
	v_mov_b64_e32 v[48:49], v[0:1]
	s_mov_b64 s[96:97], 0x4000
	v_readlane_b32 s99, v246, 58
	v_add_co_u32_e32 v64, vcc, 0xfffa0000, v192
	s_nop 1
	v_addc_co_u32_e32 v65, vcc, -1, v193, vcc
	v_add_co_u32_e32 v66, vcc, 0xfffc0000, v192
	s_nop 1
	v_addc_co_u32_e32 v67, vcc, -1, v193, vcc
	global_load_dwordx4 v[164:167], v[64:65], off
	global_load_dwordx4 v[168:171], v[66:67], off
	v_add_co_u32_e32 v64, vcc, 0xffffe000, v188
	s_nop 1
	v_addc_co_u32_e32 v65, vcc, -1, v189, vcc
	global_load_dwordx4 v[172:175], v[64:65], off
	v_add_co_u32_e32 v64, vcc, 0xffdfff80, v190
	s_nop 1
	v_addc_co_u32_e32 v65, vcc, -1, v191, vcc
	v_add_co_u32_e32 v66, vcc, 0xffffff80, v190
	s_nop 1
	v_addc_co_u32_e32 v67, vcc, -1, v191, vcc
	global_load_dwordx4 v[176:179], v[64:65], off
	global_load_dwordx4 v[180:183], v[66:67], off
	s_cmp_lt_u32 s20, s59
	s_cselect_b64 s[52:53], -1, 0
	s_cmp_ge_u32 s20, s59
	s_cselect_b64 s[50:51], -1, 0
	s_add_i32 s80, s62, s20
	s_add_i32 s100, s80, -2
	s_add_i32 s101, s63, s20
	v_add_u32_e32 v220, v213, v184
	s_waitcnt lgkmcnt(0)
	s_barrier
	s_branch .LBB0_33

; #define LAS __attribute__((address_space(3)))
; #define MFMA32(a, b, c) __builtin_amdgcn_mfma_f32_32x32x16_bf16((a), (b), (c), 0, 0, 0)
; #define ATT_LOAD(kr, vr, t) do { const bf16_t* kp_ = KVb + (size_t)(t) * 64 * 2048 + kn_off; \
;         kr[0] = *(const u32x4*)kp_; kr[1] = *(const u32x4*)(kp_ + 32 * 2048); kr[2] = *(const u32x4*)(KPEb + (t) * 64 * 64 + kp_off); \
;         const bf16_t* vp_ = VTb + (t) * 64 + v_off; vr[0] = *(const u32x4*)vp_; vr[1] = *(const u32x4*)(vp_ + 64 * SEQ); } while (0)
; #define ATT_TILE(t, slot) do { const int rel_ = (t) - 4 * qb; if (rel_ <= (w >> 1)) { qk_softmax((t), (slot), rel_ == (w >> 1)); pv(slot); } } while (0)
; DI void attn_unit(const Params& P, LAS unsigned char* lds, int b, int h, int qb, bool dry) {
;     ...
;     auto qk_softmax = [&](int kt, int kslot, bool domask) {
;         const LAS unsigned char* kb_ = Ks + kslot * KS_BYTES + r * KS_STRIDE + 16 * hh;
;         f32x16 s0, s1;
;         __builtin_amdgcn_s_setprio(1);
;         { const f32x16 z16 = {0.f, 0.f, 0.f, 0.f, 0.f, 0.f, 0.f, 0.f, 0.f, 0.f, 0.f, 0.f, 0.f, 0.f, 0.f, 0.f};
;           const bf16x8 a0 = *(const LAS bf16x8*)(kb_), a1 = *(const LAS bf16x8*)(kb_ + 32 * KS_STRIDE);
;           s0 = MFMA32(a0, qf[0], z16); s1 = MFMA32(a1, qf[0], z16); }
; #pragma unroll
;         for (int s = 1; s < 12; ++s) {
;             const bf16x8 a0 = *(const LAS bf16x8*)(kb_ + 32 * s), a1 = *(const LAS bf16x8*)(kb_ + 32 * KS_STRIDE + 32 * s);
;             s0 = MFMA32(a0, qf[s], s0); s1 = MFMA32(a1, qf[s], s1);
;         }
;         __builtin_amdgcn_s_setprio(0);
;     ...
;     for (int kt = 0; kt < nt; kt += 2) {
;         const bool more2 = kt + 2 < nt;
;         if (more2) ATT_LOAD(kB, vB, kt + 2);
;         ATT_TILE(kt, 0);
.Lattn_pfB1_skip:
	s_andn2_b64 vcc, exec, s[50:51]
	s_cmp_lt_u32 s20, s59
	s_cselect_b64 s[52:53], -1, 0
	s_cmp_ge_u32 s20, s59
	s_cselect_b64 s[50:51], -1, 0
	s_add_i32 s80, s62, s20
	s_add_i32 s100, s80, -2
	s_add_i32 s101, s63, s20
	v_add_u32_e32 v220, v213, v184
	s_barrier
	s_cbranch_vccz .LBB0_51
.LBB0_33:
	s_cmp_gt_i32 s100, s26
	s_cbranch_scc1 .LBB0_41
	s_cmp_lg_u32 s101, 2
	s_setprio 1
	ds_read_b128 v[222:225], v220
	ds_read_b128 v[226:229], v220 offset:12800
	ds_read_b128 v[230:233], v220 offset:32
	ds_read_b128 v[234:237], v220 offset:12832
	s_waitcnt lgkmcnt(3)
	v_mfma_f32_32x32x16_bf16 v[80:95], v[222:225], v[96:99], v[196:211]
	ds_read_b128 v[222:225], v220 offset:64
	s_waitcnt lgkmcnt(3)
	v_mfma_f32_32x32x16_bf16 v[64:79], v[226:229], v[96:99], v[196:211]
	ds_read_b128 v[226:229], v220 offset:12864
	s_waitcnt lgkmcnt(3)
	v_mfma_f32_32x32x16_bf16 v[80:95], v[230:233], v[100:103], v[80:95]
	ds_read_b128 v[230:233], v220 offset:96
	s_waitcnt lgkmcnt(3)
	v_mfma_f32_32x32x16_bf16 v[64:79], v[234:237], v[100:103], v[64:79]
	ds_read_b128 v[234:237], v220 offset:12896
	s_waitcnt lgkmcnt(3)
	v_mfma_f32_32x32x16_bf16 v[80:95], v[222:225], v[104:107], v[80:95]
	ds_read_b128 v[222:225], v220 offset:128
	s_waitcnt lgkmcnt(3)
	v_mfma_f32_32x32x16_bf16 v[64:79], v[226:229], v[104:107], v[64:79]
	ds_read_b128 v[226:229], v220 offset:12928
	s_waitcnt lgkmcnt(3)
	v_mfma_f32_32x32x16_bf16 v[80:95], v[230:233], v[108:111], v[80:95]
	ds_read_b128 v[230:233], v220 offset:160
	s_waitcnt lgkmcnt(3)
	v_mfma_f32_32x32x16_bf16 v[64:79], v[234:237], v[108:111], v[64:79]
	ds_read_b128 v[234:237], v220 offset:12960
	s_waitcnt lgkmcnt(3)
	v_mfma_f32_32x32x16_bf16 v[80:95], v[222:225], v[112:115], v[80:95]
	ds_read_b128 v[222:225], v220 offset:192
	s_waitcnt lgkmcnt(3)
	v_mfma_f32_32x32x16_bf16 v[64:79], v[226:229], v[112:115], v[64:79]
	ds_read_b128 v[226:229], v220 offset:12992
	s_waitcnt lgkmcnt(3)
	v_mfma_f32_32x32x16_bf16 v[80:95], v[230:233], v[116:119], v[80:95]
	ds_read_b128 v[230:233], v220 offset:224
	s_waitcnt lgkmcnt(3)
	v_mfma_f32_32x32x16_bf16 v[64:79], v[234:237], v[116:119], v[64:79]
	ds_read_b128 v[234:237], v220 offset:13024
	s_waitcnt lgkmcnt(3)
	v_mfma_f32_32x32x16_bf16 v[80:95], v[222:225], v[120:123], v[80:95]
	ds_read_b128 v[222:225], v220 offset:256
	s_waitcnt lgkmcnt(3)
	v_mfma_f32_32x32x16_bf16 v[64:79], v[226:229], v[120:123], v[64:79]
	ds_read_b128 v[226:229], v220 offset:13056
	s_waitcnt lgkmcnt(3)
	v_mfma_f32_32x32x16_bf16 v[80:95], v[230:233], v[124:127], v[80:95]
	ds_read_b128 v[230:233], v220 offset:288
	s_waitcnt lgkmcnt(3)
	v_mfma_f32_32x32x16_bf16 v[64:79], v[234:237], v[124:127], v[64:79]
	ds_read_b128 v[234:237], v220 offset:13088
	s_waitcnt lgkmcnt(3)
	v_mfma_f32_32x32x16_bf16 v[80:95], v[222:225], v[128:131], v[80:95]
	ds_read_b128 v[222:225], v220 offset:320
	s_waitcnt lgkmcnt(3)
	v_mfma_f32_32x32x16_bf16 v[64:79], v[226:229], v[128:131], v[64:79]
	ds_read_b128 v[226:229], v220 offset:13120
	s_waitcnt lgkmcnt(3)
	v_mfma_f32_32x32x16_bf16 v[80:95], v[230:233], v[132:135], v[80:95]
	ds_read_b128 v[230:233], v220 offset:352
	s_waitcnt lgkmcnt(3)
	v_mfma_f32_32x32x16_bf16 v[64:79], v[234:237], v[132:135], v[64:79]
	ds_read_b128 v[234:237], v220 offset:13152
	s_waitcnt lgkmcnt(3)
	v_mfma_f32_32x32x16_bf16 v[80:95], v[222:225], v[136:139], v[80:95]
	s_waitcnt lgkmcnt(2)
	v_mfma_f32_32x32x16_bf16 v[64:79], v[226:229], v[136:139], v[64:79]
	s_waitcnt lgkmcnt(1)
	v_mfma_f32_32x32x16_bf16 v[80:95], v[230:233], v[140:143], v[80:95]
	s_waitcnt lgkmcnt(0)
	v_mfma_f32_32x32x16_bf16 v[64:79], v[234:237], v[140:143], v[64:79]
	s_setprio 0
	s_nop 0
	s_mov_b64 vcc, s[52:53]
	s_cbranch_vccnz .Lattn_hw0_v5
	s_waitcnt vmcnt(0)
	s_branch .Lattn_hw0_go

; DI unsigned pk_bf16(float lo, float hi) { unsigned r; asm("v_cvt_pk_bf16_f32 %0, %1, %2" : "=v"(r) : "v"(lo), "v"(hi)); return r; }
; DI int obid() { int b = blockIdx.x; asm volatile("" : "+s"(b)); return b; }
; DI void attn_unit(const Params& P, LAS unsigned char* lds, int b, int h, int qb, bool dry) {
;     ...
;     float lt; { const auto rr = __builtin_amdgcn_permlane32_swap(__float_as_uint(lrun), __float_as_uint(lrun), false, false); lt = __uint_as_float(rr[0]) + __uint_as_float(rr[1]); }
;     const float inv = 1.f / lt;
;     if (dry) { float tt = 0.f;
; #pragma unroll
;         for (int d = 0; d < 4; ++d)
; #pragma unroll
;             for (int i = 0; i < 16; ++i) tt += o[d][i];
;         if (tt * inv != 123456.789f) return; }
; #pragma unroll
;     for (int d = 0; d < 4; ++d)
; #pragma unroll
;         for (int g = 0; g < 4; ++g) {
;             u32x2 ov; ov.x = pk_bf16(o[d][4 * g] * inv, o[d][4 * g + 1] * inv); ov.y = pk_bf16(o[d][4 * g + 2] * inv, o[d][4 * g + 3] * inv);
;             *(u32x2*)(qrow + 32 * d + 8 * g + 4 * hh) = ov;
;         }
; DI void phase_attn(const Params& P, LAS unsigned char* lds, bool dry) {
;     for (int item = obid(); item < 512; item += gridDim.x) {
;         const int h = item & 7, p = (item >> 3) & 31, b = item >> 8;
;         attn_unit(P, lds, b, h, 63 - p, dry);
;         attn_unit(P, lds, b, h, p, dry);
.LBB0_51:
	v_mov_b32_e32 v64, v215
	s_nop 1
	v_permlane32_swap_b32_e32 v215, v64
	v_add_f32_e32 v64, v215, v64
	v_div_scale_f32 v65, s[26:27], v64, v64, 1.0
	v_rcp_f32_e32 v66, v65
	v_lshlrev_b32_e32 v184, 1, v212
	s_and_b32 s20, s56, 31
	s_lshl_b32 s53, s20, 2
	v_fma_f32 v67, -v65, v66, 1.0
	v_fmac_f32_e32 v66, v67, v66
	v_div_scale_f32 v67, vcc, 1.0, v64, 1.0
	v_mul_f32_e32 v68, v67, v66
	v_fma_f32 v69, -v65, v68, v67
	v_fmac_f32_e32 v68, v69, v66
	v_fma_f32 v65, -v65, v68, v67
	v_div_fmas_f32 v65, v65, v66, v68
	v_div_fixup_f32 v66, v65, v64, 1.0
	v_mul_f32_e32 v32, v32, v66
	v_mul_f32_e32 v33, v33, v66
	v_mul_f32_e32 v48, v48, v66
	v_mul_f32_e32 v49, v49, v66
	v_cvt_pk_bf16_f32 v32, v32, v33
	v_mul_f32_e32 v33, v34, v66
	v_mul_f32_e32 v16, v16, v66
	v_mul_f32_e32 v17, v17, v66
	v_mul_f32_e32 v0, v0, v66
	v_mul_f32_e32 v1, v1, v66
	v_lshl_add_u64 v[64:65], v[186:187], 0, v[184:185]
	v_cvt_pk_bf16_f32 v48, v48, v49
	v_mul_f32_e32 v49, v50, v66
	v_mul_f32_e32 v34, v35, v66
	v_cvt_pk_bf16_f32 v33, v33, v34
	v_cvt_pk_bf16_f32 v16, v16, v17
	v_mul_f32_e32 v17, v18, v66
	v_cvt_pk_bf16_f32 v0, v0, v1
	v_mul_f32_e32 v1, v2, v66
	v_mul_f32_e32 v50, v51, v66
	v_cvt_pk_bf16_f32 v49, v49, v50
	global_store_dwordx2 v[64:65], v[32:33], off offset:64
	v_mul_f32_e32 v32, v36, v66
	v_mul_f32_e32 v33, v37, v66
	v_mul_f32_e32 v18, v19, v66
	v_cvt_pk_bf16_f32 v17, v17, v18
	v_mul_f32_e32 v2, v3, v66
	v_cvt_pk_bf16_f32 v1, v1, v2
	global_store_dwordx2 v[64:65], v[48:49], off
	v_mul_f32_e32 v48, v52, v66
	v_mul_f32_e32 v49, v53, v66
	v_cvt_pk_bf16_f32 v32, v32, v33
	v_mul_f32_e32 v33, v38, v66
	global_store_dwordx2 v[64:65], v[16:17], off offset:128
	v_mul_f32_e32 v16, v20, v66
	v_mul_f32_e32 v17, v21, v66
	global_store_dwordx2 v[64:65], v[0:1], off offset:192
	v_mul_f32_e32 v0, v4, v66
	v_mul_f32_e32 v1, v5, v66
	v_cvt_pk_bf16_f32 v48, v48, v49
	v_mul_f32_e32 v49, v54, v66
	v_mul_f32_e32 v34, v39, v66
	v_cvt_pk_bf16_f32 v33, v33, v34
	v_cvt_pk_bf16_f32 v16, v16, v17
	v_mul_f32_e32 v17, v22, v66
	v_cvt_pk_bf16_f32 v0, v0, v1
	v_mul_f32_e32 v1, v6, v66
	v_mul_f32_e32 v50, v55, v66
	v_cvt_pk_bf16_f32 v49, v49, v50
	global_store_dwordx2 v[64:65], v[32:33], off offset:80
	v_mul_f32_e32 v32, v40, v66
	v_mul_f32_e32 v33, v41, v66
	v_mul_f32_e32 v18, v23, v66
	v_cvt_pk_bf16_f32 v17, v17, v18
	v_mul_f32_e32 v2, v7, v66
	v_cvt_pk_bf16_f32 v1, v1, v2
	global_store_dwordx2 v[64:65], v[48:49], off offset:16
	v_mul_f32_e32 v48, v56, v66
	v_mul_f32_e32 v49, v57, v66
	v_cvt_pk_bf16_f32 v32, v32, v33
	v_mul_f32_e32 v33, v42, v66
	global_store_dwordx2 v[64:65], v[16:17], off offset:144
	v_mul_f32_e32 v16, v24, v66
	v_mul_f32_e32 v17, v25, v66
	global_store_dwordx2 v[64:65], v[0:1], off offset:208
	v_mul_f32_e32 v0, v8, v66
	v_mul_f32_e32 v1, v9, v66
	v_cvt_pk_bf16_f32 v48, v48, v49
	v_mul_f32_e32 v49, v58, v66
	v_mul_f32_e32 v34, v43, v66
	v_cvt_pk_bf16_f32 v33, v33, v34
	v_cvt_pk_bf16_f32 v16, v16, v17
	v_mul_f32_e32 v17, v26, v66
	v_cvt_pk_bf16_f32 v0, v0, v1
	v_mul_f32_e32 v1, v10, v66
	v_mul_f32_e32 v50, v59, v66
	v_cvt_pk_bf16_f32 v49, v49, v50
	global_store_dwordx2 v[64:65], v[32:33], off offset:96
	v_mul_f32_e32 v32, v44, v66
	v_mul_f32_e32 v33, v45, v66
	v_mul_f32_e32 v18, v27, v66
	v_cvt_pk_bf16_f32 v17, v17, v18
	v_mul_f32_e32 v2, v11, v66
	v_cvt_pk_bf16_f32 v1, v1, v2
	global_store_dwordx2 v[64:65], v[48:49], off offset:32
	v_mul_f32_e32 v48, v60, v66
	v_mul_f32_e32 v49, v61, v66
	v_cvt_pk_bf16_f32 v32, v32, v33
	v_mul_f32_e32 v33, v46, v66
	global_store_dwordx2 v[64:65], v[16:17], off offset:160
	v_mul_f32_e32 v16, v28, v66
	v_mul_f32_e32 v17, v29, v66
	global_store_dwordx2 v[64:65], v[0:1], off offset:224
	v_mul_f32_e32 v0, v12, v66
	v_mul_f32_e32 v1, v13, v66
	v_cvt_pk_bf16_f32 v48, v48, v49
	v_mul_f32_e32 v49, v62, v66
	v_mul_f32_e32 v34, v47, v66
	v_cvt_pk_bf16_f32 v33, v33, v34
	global_store_dwordx2 v[64:65], v[32:33], off offset:112
	v_cvt_pk_bf16_f32 v16, v16, v17
	v_mul_f32_e32 v17, v30, v66
	v_cvt_pk_bf16_f32 v0, v0, v1
	v_mul_f32_e32 v1, v14, v66
	v_mov_b32_e32 v32, v195
	v_mul_f32_e32 v50, v63, v66
	v_cvt_pk_bf16_f32 v49, v49, v50
	global_store_dwordx2 v[64:65], v[48:49], off offset:48
	v_mul_f32_e32 v18, v31, v66
	v_cvt_pk_bf16_f32 v17, v17, v18
	global_store_dwordx2 v[64:65], v[16:17], off offset:176
	v_mul_f32_e32 v2, v15, v66
	v_cvt_pk_bf16_f32 v1, v1, v2
	global_store_dwordx2 v[64:65], v[0:1], off offset:240
	s_load_dwordx8 s[60:67], s[84:85], 0xc8
	v_readfirstlane_b32 s42, v32
	s_ashr_i32 s43, s42, 1
	s_lshl_b32 s20, s35, 8
	s_andn2_b32 s43, s43, 31
	s_add_i32 s43, s43, s20
	s_sub_i32 s52, 0, s53
	s_ashr_i32 s20, s43, 31
	s_add_u32 s56, s2, s43
	s_addc_u32 s59, s3, s20
	s_lshl_b32 s35, s35, 2
	s_waitcnt lgkmcnt(0)
; #define LAS __attribute__((address_space(3)))
; DI int otid() { int t = threadIdx.x; asm volatile("" : "+v"(t)); return t; }
; DI unsigned char* ows(const Params& P) { unsigned char* p = P.ws; asm volatile("" : "+s"(p)); return p; }
; #define ATT_LOAD(kr, vr, t) do { const bf16_t* kp_ = KVb + (size_t)(t) * 64 * 2048 + kn_off; \
;         kr[0] = *(const u32x4*)kp_; kr[1] = *(const u32x4*)(kp_ + 32 * 2048); kr[2] = *(const u32x4*)(KPEb + (t) * 64 * 64 + kp_off); \
;         const bf16_t* vp_ = VTb + (t) * 64 + v_off; vr[0] = *(const u32x4*)vp_; vr[1] = *(const u32x4*)(vp_ + 64 * SEQ); } while (0)
; DI void attn_unit(const Params& P, LAS unsigned char* lds, int b, int h, int qb, bool dry) {
;     const int tid = otid(), lane = tid & 63, w = __builtin_amdgcn_readfirstlane(tid >> 6), r = lane & 31, hh = lane >> 5;
;     bf16_t* Q = (bf16_t*)(ows(P) + OFF_Q);
;     const bf16_t* KV = (const bf16_t*)(ows(P) + OFF_KV); const bf16_t* KPE = (const bf16_t*)(ows(P) + OFF_KPE); const bf16_t* VT = (const bf16_t*)(ows(P) + OFF_U);
;     LAS unsigned char* Ks = lds; LAS unsigned char* Vs = lds + 2 * KS_BYTES;
;     const int q0 = qb * 256 + w * 32;
;     bf16_t* qrow = Q + ((size_t)b * SEQ + q0 + r) * 1536 + h * 192;
;     bf16x8 qf[12];
; #pragma unroll
;     for (int s = 0; s < 12; ++s) qf[s] = *(const bf16x8*)(qrow + 16 * s + 8 * hh);
;     f32x16 o[4];
; #pragma unroll
;     for (int d = 0; d < 4; ++d)
; #pragma unroll
;         for (int i = 0; i < 16; ++i) o[d][i] = 0.f;
;     float mrun = -INFINITY, lrun = 0.f;
;     const int nt = 4 * (qb + 1);
;     const bf16_t* KVb = KV + (size_t)b * SEQ * 2048 + h * 256; const bf16_t* KPEb = KPE + (size_t)b * SEQ * 64; const bf16_t* VTb = VT + (size_t)(b * 8 + h) * 128 * SEQ;
;     const int kn_off = (tid >> 4) * 2048 + (tid & 15) * 8, kn_dst = (tid >> 4) * KS_STRIDE + (tid & 15) * 16;
;     const int kp_off = (tid >> 3) * 64 + (tid & 7) * 8, kp_dst = (tid >> 3) * KS_STRIDE + 256 + (tid & 7) * 16;
;     const int v_off = (tid >> 3) * SEQ + (tid & 7) * 8, v_dst = (tid >> 3) * VS_STRIDE + (tid & 7) * 16;
;     ...
;     ATT_LOAD(kA, vA, 0);
;     __syncthreads();
;     ATT_STORE(kA, vA, 0);
;     ATT_LOAD(kA, vA, 1);
	s_mov_b64 s[50:51], s[66:67]
	s_mov_b64 s[26:27], s[66:67]
	s_lshl_b32 s20, s36, 1
	s_add_i32 s35, s35, 4
	v_and_b32_e32 v35, 15, v32
	s_add_u32 s2, s26, s44
	v_ashrrev_i32_e32 v34, 4, v32
	v_lshlrev_b32_e32 v0, 3, v35
	v_and_b32_e32 v37, 7, v32
	s_addc_u32 s3, s27, s45
	s_lshl_b32 s36, s37, 1
	v_lshl_or_b32 v0, v34, 11, v0
	v_ashrrev_i32_e32 v36, 3, v32
	v_lshlrev_b32_e32 v1, 3, v37
	s_add_u32 s2, s2, s36
	v_lshl_or_b32 v8, v36, 6, v1
	v_lshl_or_b32 v12, v36, 14, v1
	v_ashrrev_i32_e32 v1, 31, v0
	s_addc_u32 s3, s3, 0
	v_lshlrev_b64 v[20:21], 1, v[0:1]
	s_mov_b64 s[62:63], s[66:67]
	s_mov_b64 s[40:41], s[66:67]
	v_lshl_add_u64 v[22:23], s[2:3], 0, v[20:21]
	s_mov_b32 s2, 0x13808000
	s_add_u32 s36, s40, s46
	v_add_co_u32_e32 v0, vcc, s2, v22
	s_addc_u32 s37, s41, s47
	s_nop 0
	v_addc_co_u32_e32 v1, vcc, 0, v23, vcc
	s_mov_b32 s2, 0x13828000
	v_add_co_u32_e32 v4, vcc, s2, v22
	s_add_u32 s2, s62, s30
	v_ashrrev_i32_e32 v9, 31, v8
	s_addc_u32 s3, s63, s31
	v_addc_co_u32_e32 v5, vcc, 0, v23, vcc
	v_lshl_add_u64 v[24:25], v[8:9], 1, s[2:3]
	s_mov_b32 s2, 0xd408000
	v_ashrrev_i32_e32 v13, 31, v12
	v_add_co_u32_e32 v8, vcc, s2, v24
	v_lshlrev_b64 v[26:27], 1, v[12:13]
	global_load_dwordx4 v[0:3], v[0:1], off
	s_nop 0
	global_load_dwordx4 v[4:7], v[4:5], off
	v_addc_co_u32_e32 v9, vcc, 0, v25, vcc
	v_lshl_add_u64 v[28:29], s[36:37], 0, v[26:27]
	s_mov_b32 s2, 0x5808000
	v_add_co_u32_e32 v12, vcc, s2, v28
	s_mov_b32 s2, 0x5a08000
	s_nop 0
	v_addc_co_u32_e32 v13, vcc, 0, v29, vcc
	v_add_co_u32_e32 v30, vcc, s2, v28
	global_load_dwordx4 v[8:11], v[8:9], off
	s_nop 0
	v_addc_co_u32_e32 v31, vcc, 0, v29, vcc
	global_load_dwordx4 v[12:15], v[12:13], off
	v_and_b32_e32 v38, 31, v32
	global_load_dwordx4 v[16:19], v[30:31], off
	v_bfe_u32 v39, v32, 5, 1
	v_or_b32_e32 v40, s56, v38
	v_mov_b64_e32 v[32:33], s[50:51]
	v_mad_u64_u32 v[32:33], s[2:3], v40, s39, v[32:33]
	v_mad_i32_i24 v33, s59, v248, v33
	v_lshl_add_u64 v[32:33], v[32:33], 0, s[20:21]
	s_mov_b64 s[2:3], 0xd808000
	v_lshl_add_u64 v[186:187], v[32:33], 0, s[2:3]
	v_lshlrev_b32_e32 v184, 4, v39
	v_lshl_add_u64 v[32:33], v[186:187], 0, v[184:185]
	global_load_dwordx4 v[96:99], v[32:33], off
	global_load_dwordx4 v[100:103], v[32:33], off offset:32
	global_load_dwordx4 v[104:107], v[32:33], off offset:64
	global_load_dwordx4 v[108:111], v[32:33], off offset:96
	global_load_dwordx4 v[112:115], v[32:33], off offset:128
	global_load_dwordx4 v[116:119], v[32:33], off offset:160
	global_load_dwordx4 v[120:123], v[32:33], off offset:192
	global_load_dwordx4 v[124:127], v[32:33], off offset:224
	global_load_dwordx4 v[128:131], v[32:33], off offset:256
	global_load_dwordx4 v[132:135], v[32:33], off offset:288
	global_load_dwordx4 v[136:139], v[32:33], off offset:320
	global_load_dwordx4 v[140:143], v[32:33], off offset:352
	v_mul_lo_u32 v32, v34, s29
	v_lshl_add_u32 v33, v35, 4, v32
	v_lshlrev_b32_e32 v32, 4, v37
	v_mad_u64_u32 v[34:35], s[2:3], v36, s68, v[32:33]
	s_mov_b64 s[2:3], 0x5808000
	s_nop 0
	v_lshl_add_u64 v[28:29], v[28:29], 0, s[2:3]
	v_add_u32_e32 v250, 0, v33
	s_movk_i32 s2, 0x108
	s_waitcnt lgkmcnt(0)
	s_barrier
; #define ATT_LOAD(kr, vr, t) do { const bf16_t* kp_ = KVb + (size_t)(t) * 64 * 2048 + kn_off; \
;         kr[0] = *(const u32x4*)kp_; kr[1] = *(const u32x4*)(kp_ + 32 * 2048); kr[2] = *(const u32x4*)(KPEb + (t) * 64 * 64 + kp_off); \
;         const bf16_t* vp_ = VTb + (t) * 64 + v_off; vr[0] = *(const u32x4*)vp_; vr[1] = *(const u32x4*)(vp_ + 64 * SEQ); } while (0)
; DI void attn_unit(const Params& P, LAS unsigned char* lds, int b, int h, int qb, bool dry) {
;     ...
;     f32x16 o[4];
; #pragma unroll
;     for (int d = 0; d < 4; ++d)
; #pragma unroll
;         for (int i = 0; i < 16; ++i) o[d][i] = 0.f;
;     float mrun = -INFINITY, lrun = 0.f;
;     const int nt = 4 * (qb + 1);
;     const bf16_t* KVb = KV + (size_t)b * SEQ * 2048 + h * 256; const bf16_t* KPEb = KPE + (size_t)b * SEQ * 64; const bf16_t* VTb = VT + (size_t)(b * 8 + h) * 128 * SEQ;
;     const int kn_off = (tid >> 4) * 2048 + (tid & 15) * 8, kn_dst = (tid >> 4) * KS_STRIDE + (tid & 15) * 16;
;     const int kp_off = (tid >> 3) * 64 + (tid & 7) * 8, kp_dst = (tid >> 3) * KS_STRIDE + 256 + (tid & 7) * 16;
;     const int v_off = (tid >> 3) * SEQ + (tid & 7) * 8, v_dst = (tid >> 3) * VS_STRIDE + (tid & 7) * 16;
;     ...
;     ATT_LOAD(kA, vA, 0);
;     __syncthreads();
;     ATT_STORE(kA, vA, 0);
;     ATT_LOAD(kA, vA, 1);
;     __syncthreads();
;     for (int kt = 0; kt < nt; kt += 2) {
;         const bool more2 = kt + 2 < nt;
;         if (more2) ATT_LOAD(kB, vB, kt + 2);
	s_waitcnt vmcnt(0)
	ds_write_b128 v250, v[0:3]
	ds_write_b128 v250, v[4:7] offset:12800
	v_mad_u64_u32 v[0:1], s[2:3], v36, s2, v[34:35]
	s_mov_b32 s2, 0x13848000
	v_add_u32_e32 v251, 0, v0
	v_add_co_u32_e32 v0, vcc, s2, v22
	v_add_u32_e32 v252, 0, v34
	s_nop 0
	v_addc_co_u32_e32 v1, vcc, 0, v23, vcc
	s_mov_b32 s2, 0x13868000
	v_add_u32_e32 v253, 0xc800, v252
	v_add_u32_e32 v254, 0xea00, v252
	v_add_co_u32_e32 v2, vcc, s2, v22
	ds_write_b128 v251, v[8:11] offset:256
	ds_write2_b64 v253, v[12:13], v[14:15] offset1:1
	ds_write2_b64 v254, v[16:17], v[18:19] offset1:1
	v_addc_co_u32_e32 v3, vcc, 0, v23, vcc
	s_mov_b32 s2, 0xd40a000
	global_load_dwordx4 v[144:147], v[0:1], off
	global_load_dwordx4 v[148:151], v[2:3], off
	v_add_co_u32_e32 v0, vcc, s2, v24
	v_mad_u32_u24 v213, v38, s29, 0
	s_nop 0
	v_addc_co_u32_e32 v1, vcc, 0, v25, vcc
	global_load_dwordx4 v[152:155], v[0:1], off
	global_load_dwordx4 v[156:159], v[28:29], off offset:128
	global_load_dwordx4 v[160:163], v[30:31], off offset:128
	s_movk_i32 s2, 0xfef8
	v_mad_i32_i24 v19, v38, s2, v213
	v_mad_u64_u32 v[16:17], s[2:3], v36, s29, v[32:33]
	v_readlane_b32 s2, v246, 47
	s_ashr_i32 s36, s42, 7
	v_lshlrev_b32_e32 v18, 3, v39
	v_mov_b32_e32 v0, s2
	s_mov_b64 s[2:3], 0xd40e000
	v_lshl_add_u64 v[188:189], v[24:25], 0, s[2:3]
	s_add_u32 s2, s40, s48
	s_addc_u32 s3, s41, s49
	v_mad_u32_u24 v17, v38, s68, v0
	v_lshl_add_u64 v[0:1], s[2:3], 0, v[26:27]
	s_mov_b64 s[2:3], 0x5a08180
	v_lshl_add_u64 v[190:191], v[0:1], 0, s[2:3]
	s_add_u32 s2, s26, s57
	s_addc_u32 s3, s27, s58
	v_lshl_add_u64 v[0:1], s[2:3], 0, v[20:21]
	s_mov_b64 s[2:3], 0x138e8000
	v_mov_b32_e32 v14, v185
	v_mov_b32_e32 v15, v185
	v_or_b32_e32 v214, s43, v38
	v_lshlrev_b32_e32 v212, 2, v39
	v_lshl_add_u64 v[192:193], v[0:1], 0, s[2:3]
	s_add_i32 s2, s36, s53
	v_mov_b32_e32 v0, v185
	v_mov_b32_e32 v1, v185
	v_mov_b32_e32 v2, v185
	v_mov_b32_e32 v3, v185
	v_mov_b32_e32 v4, v185
	v_mov_b32_e32 v5, v185
	v_mov_b32_e32 v6, v185
	v_mov_b32_e32 v7, v185
	v_mov_b32_e32 v8, v185
	v_mov_b32_e32 v9, v185
	v_mov_b32_e32 v10, v185
	v_mov_b32_e32 v11, v185
	v_mov_b32_e32 v12, v185
	v_mov_b32_e32 v13, v185
	v_add_u32_e32 v216, v19, v18
	v_add_u32_e32 v217, 0, v16
	v_add_u32_e32 v218, v17, v18
	v_mov_b64_e32 v[30:31], v[14:15]
	v_mov_b64_e32 v[46:47], v[14:15]
	v_mov_b64_e32 v[62:63], v[14:15]
	s_mov_b32 s20, 2
	s_sub_i32 s26, 1, s2
	s_sub_i32 s27, 0, s2
	v_mov_b32_e32 v194, 0xff800000
	v_mov_b32_e32 v196, 0
	v_mov_b32_e32 v197, 0
	v_mov_b32_e32 v198, 0
	v_mov_b32_e32 v199, 0
	v_mov_b32_e32 v200, 0
	v_mov_b32_e32 v201, 0
	v_mov_b32_e32 v202, 0
	v_mov_b32_e32 v203, 0
	v_mov_b32_e32 v204, 0
	v_mov_b32_e32 v205, 0
	v_mov_b32_e32 v206, 0
	v_mov_b32_e32 v207, 0
	v_mov_b32_e32 v208, 0
	v_mov_b32_e32 v209, 0
	v_mov_b32_e32 v210, 0
	v_mov_b32_e32 v211, 0
	v_mov_b32_e32 v215, 0
	v_mov_b32_e32 v219, v212
	v_mov_b64_e32 v[28:29], v[12:13]
	v_mov_b64_e32 v[26:27], v[10:11]
	v_mov_b64_e32 v[24:25], v[8:9]
	v_mov_b64_e32 v[22:23], v[6:7]
	v_mov_b64_e32 v[20:21], v[4:5]
	v_mov_b64_e32 v[18:19], v[2:3]
	v_mov_b64_e32 v[16:17], v[0:1]
	v_mov_b64_e32 v[44:45], v[12:13]
	v_mov_b64_e32 v[42:43], v[10:11]
	v_mov_b64_e32 v[40:41], v[8:9]
	v_mov_b64_e32 v[38:39], v[6:7]
	v_mov_b64_e32 v[36:37], v[4:5]
	v_mov_b64_e32 v[34:35], v[2:3]
	v_mov_b64_e32 v[32:33], v[0:1]
	v_mov_b64_e32 v[60:61], v[12:13]
	v_mov_b64_e32 v[58:59], v[10:11]
	v_mov_b64_e32 v[56:57], v[8:9]
	v_mov_b64_e32 v[54:55], v[6:7]
	v_mov_b64_e32 v[52:53], v[4:5]
	v_mov_b64_e32 v[50:51], v[2:3]
	v_mov_b64_e32 v[48:49], v[0:1]
	s_mov_b64 s[60:61], 0
	v_add_co_u32_e32 v64, vcc, 0xfffa0000, v192
	s_nop 1
	v_addc_co_u32_e32 v65, vcc, -1, v193, vcc
	v_add_co_u32_e32 v66, vcc, 0xfffc0000, v192
	s_nop 1
	v_addc_co_u32_e32 v67, vcc, -1, v193, vcc
	global_load_dwordx4 v[164:167], v[64:65], off
	global_load_dwordx4 v[168:171], v[66:67], off
	v_add_co_u32_e32 v64, vcc, 0xffffe000, v188
	s_nop 1
	v_addc_co_u32_e32 v65, vcc, -1, v189, vcc
	global_load_dwordx4 v[172:175], v[64:65], off
	v_add_co_u32_e32 v64, vcc, 0xffdfff80, v190
	s_nop 1
	v_addc_co_u32_e32 v65, vcc, -1, v191, vcc
	v_add_co_u32_e32 v66, vcc, 0xffffff80, v190
	s_nop 1
	v_addc_co_u32_e32 v67, vcc, -1, v191, vcc
	global_load_dwordx4 v[176:179], v[64:65], off
	global_load_dwordx4 v[180:183], v[66:67], off
	s_cmp_lt_u32 s20, s35
	s_cselect_b64 s[30:31], -1, 0
	s_cmp_ge_u32 s20, s35
	s_cselect_b64 s[2:3], -1, 0
	s_add_i32 s37, s52, s20
	s_add_i32 s100, s37, -2
	s_add_i32 s101, s27, s20
	v_add_u32_e32 v220, v213, v184
	s_waitcnt lgkmcnt(0)
	s_barrier
	s_branch .LBB0_53

; #define LAS __attribute__((address_space(3)))
; #define MFMA32(a, b, c) __builtin_amdgcn_mfma_f32_32x32x16_bf16((a), (b), (c), 0, 0, 0)
; #define ATT_LOAD(kr, vr, t) do { const bf16_t* kp_ = KVb + (size_t)(t) * 64 * 2048 + kn_off; \
;         kr[0] = *(const u32x4*)kp_; kr[1] = *(const u32x4*)(kp_ + 32 * 2048); kr[2] = *(const u32x4*)(KPEb + (t) * 64 * 64 + kp_off); \
;         const bf16_t* vp_ = VTb + (t) * 64 + v_off; vr[0] = *(const u32x4*)vp_; vr[1] = *(const u32x4*)(vp_ + 64 * SEQ); } while (0)
; #define ATT_TILE(t, slot) do { const int rel_ = (t) - 4 * qb; if (rel_ <= (w >> 1)) { qk_softmax((t), (slot), rel_ == (w >> 1)); pv(slot); } } while (0)
; DI void attn_unit(const Params& P, LAS unsigned char* lds, int b, int h, int qb, bool dry) {
;     ...
;     auto qk_softmax = [&](int kt, int kslot, bool domask) {
;         const LAS unsigned char* kb_ = Ks + kslot * KS_BYTES + r * KS_STRIDE + 16 * hh;
;         f32x16 s0, s1;
;         __builtin_amdgcn_s_setprio(1);
;         { const f32x16 z16 = {0.f, 0.f, 0.f, 0.f, 0.f, 0.f, 0.f, 0.f, 0.f, 0.f, 0.f, 0.f, 0.f, 0.f, 0.f, 0.f};
;           const bf16x8 a0 = *(const LAS bf16x8*)(kb_), a1 = *(const LAS bf16x8*)(kb_ + 32 * KS_STRIDE);
;           s0 = MFMA32(a0, qf[0], z16); s1 = MFMA32(a1, qf[0], z16); }
; #pragma unroll
;         for (int s = 1; s < 12; ++s) {
;             const bf16x8 a0 = *(const LAS bf16x8*)(kb_ + 32 * s), a1 = *(const LAS bf16x8*)(kb_ + 32 * KS_STRIDE + 32 * s);
;             s0 = MFMA32(a0, qf[s], s0); s1 = MFMA32(a1, qf[s], s1);
;         }
;         __builtin_amdgcn_s_setprio(0);
;     ...
;     for (int kt = 0; kt < nt; kt += 2) {
;         const bool more2 = kt + 2 < nt;
;         if (more2) ATT_LOAD(kB, vB, kt + 2);
;         ATT_TILE(kt, 0);
.Lattn_pfB2_skip:
	s_andn2_b64 vcc, exec, s[2:3]
	s_cmp_lt_u32 s20, s35
	s_cselect_b64 s[30:31], -1, 0
	s_cmp_ge_u32 s20, s35
	s_cselect_b64 s[2:3], -1, 0
	s_add_i32 s37, s52, s20
	s_add_i32 s100, s37, -2
	s_add_i32 s101, s27, s20
	v_add_u32_e32 v220, v213, v184
	s_barrier
	s_cbranch_vccz .LBB0_30
.LBB0_53:
	s_cmp_gt_i32 s100, s36
	s_cbranch_scc1 .LBB0_61
	s_cmp_lg_u32 s101, 2
	s_setprio 1
	ds_read_b128 v[222:225], v220
	ds_read_b128 v[226:229], v220 offset:12800
	ds_read_b128 v[230:233], v220 offset:32
	ds_read_b128 v[234:237], v220 offset:12832
	s_waitcnt lgkmcnt(3)
	v_mfma_f32_32x32x16_bf16 v[80:95], v[222:225], v[96:99], v[196:211]
	ds_read_b128 v[222:225], v220 offset:64
	s_waitcnt lgkmcnt(3)
	v_mfma_f32_32x32x16_bf16 v[64:79], v[226:229], v[96:99], v[196:211]
	ds_read_b128 v[226:229], v220 offset:12864
	s_waitcnt lgkmcnt(3)
	v_mfma_f32_32x32x16_bf16 v[80:95], v[230:233], v[100:103], v[80:95]
	ds_read_b128 v[230:233], v220 offset:96
	s_waitcnt lgkmcnt(3)
	v_mfma_f32_32x32x16_bf16 v[64:79], v[234:237], v[100:103], v[64:79]
	ds_read_b128 v[234:237], v220 offset:12896
	s_waitcnt lgkmcnt(3)
	v_mfma_f32_32x32x16_bf16 v[80:95], v[222:225], v[104:107], v[80:95]
	ds_read_b128 v[222:225], v220 offset:128
	s_waitcnt lgkmcnt(3)
	v_mfma_f32_32x32x16_bf16 v[64:79], v[226:229], v[104:107], v[64:79]
	ds_read_b128 v[226:229], v220 offset:12928
	s_waitcnt lgkmcnt(3)
	v_mfma_f32_32x32x16_bf16 v[80:95], v[230:233], v[108:111], v[80:95]
	ds_read_b128 v[230:233], v220 offset:160
	s_waitcnt lgkmcnt(3)
	v_mfma_f32_32x32x16_bf16 v[64:79], v[234:237], v[108:111], v[64:79]
	ds_read_b128 v[234:237], v220 offset:12960
	s_waitcnt lgkmcnt(3)
	v_mfma_f32_32x32x16_bf16 v[80:95], v[222:225], v[112:115], v[80:95]
	ds_read_b128 v[222:225], v220 offset:192
	s_waitcnt lgkmcnt(3)
	v_mfma_f32_32x32x16_bf16 v[64:79], v[226:229], v[112:115], v[64:79]
	ds_read_b128 v[226:229], v220 offset:12992
	s_waitcnt lgkmcnt(3)
	v_mfma_f32_32x32x16_bf16 v[80:95], v[230:233], v[116:119], v[80:95]
	ds_read_b128 v[230:233], v220 offset:224
	s_waitcnt lgkmcnt(3)
	v_mfma_f32_32x32x16_bf16 v[64:79], v[234:237], v[116:119], v[64:79]
	ds_read_b128 v[234:237], v220 offset:13024
	s_waitcnt lgkmcnt(3)
	v_mfma_f32_32x32x16_bf16 v[80:95], v[222:225], v[120:123], v[80:95]
	ds_read_b128 v[222:225], v220 offset:256
	s_waitcnt lgkmcnt(3)
	v_mfma_f32_32x32x16_bf16 v[64:79], v[226:229], v[120:123], v[64:79]
	ds_read_b128 v[226:229], v220 offset:13056
	s_waitcnt lgkmcnt(3)
	v_mfma_f32_32x32x16_bf16 v[80:95], v[230:233], v[124:127], v[80:95]
	ds_read_b128 v[230:233], v220 offset:288
	s_waitcnt lgkmcnt(3)
	v_mfma_f32_32x32x16_bf16 v[64:79], v[234:237], v[124:127], v[64:79]
	ds_read_b128 v[234:237], v220 offset:13088
	s_waitcnt lgkmcnt(3)
	v_mfma_f32_32x32x16_bf16 v[80:95], v[222:225], v[128:131], v[80:95]
	ds_read_b128 v[222:225], v220 offset:320
	s_waitcnt lgkmcnt(3)
	v_mfma_f32_32x32x16_bf16 v[64:79], v[226:229], v[128:131], v[64:79]
	ds_read_b128 v[226:229], v220 offset:13120
	s_waitcnt lgkmcnt(3)
	v_mfma_f32_32x32x16_bf16 v[80:95], v[230:233], v[132:135], v[80:95]
	ds_read_b128 v[230:233], v220 offset:352
	s_waitcnt lgkmcnt(3)
	v_mfma_f32_32x32x16_bf16 v[64:79], v[234:237], v[132:135], v[64:79]
	ds_read_b128 v[234:237], v220 offset:13152
	s_waitcnt lgkmcnt(3)
	v_mfma_f32_32x32x16_bf16 v[80:95], v[222:225], v[136:139], v[80:95]
	s_waitcnt lgkmcnt(2)
	v_mfma_f32_32x32x16_bf16 v[64:79], v[226:229], v[136:139], v[64:79]
	s_waitcnt lgkmcnt(1)
	v_mfma_f32_32x32x16_bf16 v[80:95], v[230:233], v[140:143], v[80:95]
	s_waitcnt lgkmcnt(0)
	v_mfma_f32_32x32x16_bf16 v[64:79], v[234:237], v[140:143], v[64:79]
	s_setprio 0
	s_nop 0
	s_mov_b64 vcc, s[30:31]
	s_cbranch_vccnz .Lattn_hw2_v5
	s_waitcnt vmcnt(0)
	s_branch .Lattn_hw2_go
